# fox unmasked loop: decay sub/fma pairs packed into v_pk_add_f32 / v_pk_fma_f32 (32 fewer VALU per tile)
# speedup vs baseline: 1.0035x; 1.0035x over previous
.LBB0_969:
	s_cmp_lt_i32 s83, s7
	s_cselect_b64 s[18:19], -1, 0
	s_and_b64 s[34:35], s[18:19], exec
	s_cselect_b32 s2, 0x98000, 0
	s_cmp_lg_u64 s[18:19], 0
	v_add_u32_e32 v186, s2, v186
	v_add_u32_e32 v187, s2, v187
	s_addc_u32 s83, s83, 0
	v_lshl_add_u32 v181, s57, 14, v15
	v_lshl_add_u32 v213, s13, 8, v212
	v_add_u32_e32 v10, v181, v188
	ds_read_b128 v[2:5], v213
	ds_read_b128 v[6:9], v10
	ds_read_b128 v[10:13], v10 offset:8192
	s_waitcnt lgkmcnt(0)
	v_mfma_f32_32x32x16_bf16 v[112:127], v[6:9], v[144:147], 0
	v_pk_add_f32 v[2:3], v[180:181], v[2:3] op_sel_hi:[0,1] neg_lo:[0,1] neg_hi:[0,1]
	v_pk_add_f32 v[4:5], v[180:181], v[4:5] op_sel_hi:[0,1] neg_lo:[0,1] neg_hi:[0,1]
	v_pk_fma_f32 v[2:3], v[96:97], s[92:93], v[2:3] op_sel_hi:[1,0,1]
	v_pk_fma_f32 v[4:5], v[98:99], s[92:93], v[4:5] op_sel_hi:[1,0,1]
	v_exp_f32_e32 v214, v2
	v_exp_f32_e32 v215, v3
	v_exp_f32_e32 v222, v4
	v_exp_f32_e32 v223, v5
	v_mfma_f32_32x32x16_bf16 v[128:143], v[10:13], v[144:147], 0
	ds_read_b128 v[2:5], v213 offset:32
	v_add_u32_e32 v10, v181, v189
	ds_read_b128 v[6:9], v10
	ds_read_b128 v[10:13], v10 offset:8192
	s_waitcnt lgkmcnt(0)
	v_mfma_f32_32x32x16_bf16 v[128:143], v[10:13], v[148:151], v[128:143]
	v_pk_add_f32 v[2:3], v[180:181], v[2:3] op_sel_hi:[0,1] neg_lo:[0,1] neg_hi:[0,1]
	v_pk_add_f32 v[4:5], v[180:181], v[4:5] op_sel_hi:[0,1] neg_lo:[0,1] neg_hi:[0,1]
	v_pk_fma_f32 v[2:3], v[100:101], s[92:93], v[2:3] op_sel_hi:[1,0,1]
	v_pk_fma_f32 v[4:5], v[102:103], s[92:93], v[4:5] op_sel_hi:[1,0,1]
	v_exp_f32_e32 v100, v2
	v_exp_f32_e32 v101, v3
	v_exp_f32_e32 v102, v4
	v_exp_f32_e32 v103, v5
	v_cvt_pk_bf16_f32 v2, v214, v215
	v_cvt_pk_bf16_f32 v3, v222, v223
	v_cvt_pk_bf16_f32 v4, v100, v101
	v_cvt_pk_bf16_f32 v5, v102, v103
	s_nop 0
	v_permlane32_swap_b32_e32 v2, v4
	v_permlane32_swap_b32_e32 v3, v5
	v_mfma_f32_32x32x16_bf16 v[112:127], v[6:9], v[148:151], v[112:127]
	ds_read_b128 v[6:9], v213 offset:64
	v_add_u32_e32 v96, v181, v190
	ds_read_b128 v[10:13], v96
	ds_read_b128 v[96:99], v96 offset:8192
	s_waitcnt lgkmcnt(0)
	v_mfma_f32_32x32x16_bf16 v[112:127], v[10:13], v[152:155], v[112:127]
	v_pk_add_f32 v[6:7], v[180:181], v[6:7] op_sel_hi:[0,1] neg_lo:[0,1] neg_hi:[0,1]
	v_pk_fma_f32 v[6:7], v[104:105], s[92:93], v[6:7] op_sel_hi:[1,0,1]
	v_pk_add_f32 v[8:9], v[180:181], v[8:9] op_sel_hi:[0,1] neg_lo:[0,1] neg_hi:[0,1]
	v_pk_fma_f32 v[8:9], v[106:107], s[92:93], v[8:9] op_sel_hi:[1,0,1]
	v_exp_f32_e32 v104, v6
	v_exp_f32_e32 v105, v7
	v_pk_add_f32 v[6:7], v[182:183], v[214:215]
	v_exp_f32_e32 v182, v8
	v_pk_add_f32 v[6:7], v[222:223], v[6:7]
	v_exp_f32_e32 v183, v9
	v_pk_add_f32 v[6:7], v[6:7], v[100:101]
	v_mfma_f32_32x32x16_bf16 v[128:143], v[96:99], v[152:155], v[128:143]
	v_add_f32_e64 v6, v102, v6
	v_add_f32_e64 v7, v103, v7
	v_add_f32_e64 v106, v6, v104
	v_add_f32_e64 v107, v7, v105
	ds_read_b128 v[6:9], v213 offset:96
	v_add_u32_e32 v96, v181, v191
	ds_read_b128 v[10:13], v96
	ds_read_b128 v[96:99], v96 offset:8192
	s_waitcnt lgkmcnt(0)
	v_mfma_f32_32x32x16_bf16 v[128:143], v[96:99], v[156:159], v[128:143]
	v_pk_add_f32 v[6:7], v[180:181], v[6:7] op_sel_hi:[0,1] neg_lo:[0,1] neg_hi:[0,1]
	v_pk_add_f32 v[8:9], v[180:181], v[8:9] op_sel_hi:[0,1] neg_lo:[0,1] neg_hi:[0,1]
	v_pk_fma_f32 v[6:7], v[108:109], s[92:93], v[6:7] op_sel_hi:[1,0,1]
	v_pk_fma_f32 v[8:9], v[110:111], s[92:93], v[8:9] op_sel_hi:[1,0,1]
	v_exp_f32_e32 v108, v6
	v_exp_f32_e32 v109, v7
	v_exp_f32_e32 v110, v8
	v_exp_f32_e32 v111, v9
	v_cvt_pk_bf16_f32 v6, v104, v105
	v_cvt_pk_bf16_f32 v7, v182, v183
	v_cvt_pk_bf16_f32 v8, v108, v109
	v_cvt_pk_bf16_f32 v9, v110, v111
	s_nop 0
	v_permlane32_swap_b32_e32 v6, v8
	v_permlane32_swap_b32_e32 v7, v9
	v_mfma_f32_32x32x16_bf16 v[112:127], v[10:13], v[156:159], v[112:127]
	v_add_u32_e32 v100, v181, v192
	ds_read_b128 v[10:13], v213 offset:128
	ds_read_b128 v[96:99], v100
	ds_read_b128 v[100:103], v100 offset:8192
	s_waitcnt lgkmcnt(0)
	v_mfma_f32_32x32x16_bf16 v[112:127], v[96:99], v[160:163], v[112:127]
	v_pk_add_f32 v[10:11], v[180:181], v[10:11] op_sel_hi:[0,1] neg_lo:[0,1] neg_hi:[0,1]
	v_pk_fma_f32 v[10:11], v[80:81], s[92:93], v[10:11] op_sel_hi:[1,0,1]
	v_exp_f32_e32 v104, v10
	v_exp_f32_e32 v105, v11
	v_pk_add_f32 v[12:13], v[180:181], v[12:13] op_sel_hi:[0,1] neg_lo:[0,1] neg_hi:[0,1]
	v_pk_fma_f32 v[12:13], v[82:83], s[92:93], v[12:13] op_sel_hi:[1,0,1]
	v_exp_f32_e32 v214, v12
	v_exp_f32_e32 v215, v13
	v_mfma_f32_32x32x16_bf16 v[128:143], v[100:103], v[160:163], v[128:143]
	ds_read_b128 v[10:13], v213 offset:160
	v_add_u32_e32 v96, v181, v193
	ds_read_b128 v[80:83], v96
	ds_read_b128 v[96:99], v96 offset:8192
	s_waitcnt lgkmcnt(0)
	v_mfma_f32_32x32x16_bf16 v[128:143], v[96:99], v[164:167], v[128:143]
	v_pk_add_f32 v[10:11], v[180:181], v[10:11] op_sel_hi:[0,1] neg_lo:[0,1] neg_hi:[0,1]
	v_pk_add_f32 v[12:13], v[180:181], v[12:13] op_sel_hi:[0,1] neg_lo:[0,1] neg_hi:[0,1]
	v_pk_fma_f32 v[10:11], v[84:85], s[92:93], v[10:11] op_sel_hi:[1,0,1]
	v_pk_fma_f32 v[12:13], v[86:87], s[92:93], v[12:13] op_sel_hi:[1,0,1]
	v_exp_f32_e32 v100, v10
	v_exp_f32_e32 v101, v11
	v_exp_f32_e32 v102, v12
	v_exp_f32_e32 v103, v13
	v_cvt_pk_bf16_f32 v10, v104, v105
	v_cvt_pk_bf16_f32 v11, v214, v215
	v_cvt_pk_bf16_f32 v12, v100, v101
	v_cvt_pk_bf16_f32 v13, v102, v103
	s_nop 0
	v_permlane32_swap_b32_e32 v10, v12
	v_permlane32_swap_b32_e32 v11, v13
	v_mfma_f32_32x32x16_bf16 v[112:127], v[80:83], v[164:167], v[112:127]
	v_add_u32_e32 v96, v181, v194
	ds_read_b128 v[80:83], v213 offset:192
	ds_read_b128 v[84:87], v96
	ds_read_b128 v[96:99], v96 offset:8192
	s_waitcnt lgkmcnt(0)
; #define SBAR() __builtin_amdgcn_sched_barrier(0)
; #define VSET(S, d0) do { constexpr int b_ = (d0) * 512; TRRD(S##l0, b_); TRRD(S##h0, b_ + 2048); TRRD(S##l1, b_ + 4096); TRRD(S##h1, b_ + 6144); \
;         TRRD(S##l2, b_ + 8192); TRRD(S##h2, b_ + 10240); TRRD(S##l3, b_ + 12288); TRRD(S##h3, b_ + 14336); } while (0)
; #define LWAIT(n) do { asm volatile("s_waitcnt lgkmcnt(" #n ")" ::: "memory"); SBAR(); } while (0)
; __device__ __forceinline__ void pv_tile(f32x16* o, unsigned vb, bf16x8 pa0, bf16x8 pa1, bf16x8 pa2, bf16x8 pa3) {
;     ...
;     s16x4 Al0, Al1, Al2, Al3, Ah0, Ah1, Ah2, Ah3, Bl0, Bl1, Bl2, Bl3, Bh0, Bh1, Bh2, Bh3;
;     VSET(A, 0);
;     VSET(B, 1); LWAIT(8); VMMA(A, 0); SBAR();
;     VSET(A, 2); LWAIT(8); VMMA(B, 1); SBAR();
;     VSET(B, 3); LWAIT(8); VMMA(A, 2); SBAR();
;     LWAIT(0); VMMA(B, 3);
	v_mfma_f32_32x32x16_bf16 v[112:127], v[84:87], v[168:171], v[112:127]
	v_pk_add_f32 v[80:81], v[180:181], v[80:81] op_sel_hi:[0,1] neg_lo:[0,1] neg_hi:[0,1]
	v_pk_add_f32 v[82:83], v[180:181], v[82:83] op_sel_hi:[0,1] neg_lo:[0,1] neg_hi:[0,1]
	v_pk_fma_f32 v[80:81], v[88:89], s[92:93], v[80:81] op_sel_hi:[1,0,1]
	v_pk_fma_f32 v[82:83], v[90:91], s[92:93], v[82:83] op_sel_hi:[1,0,1]
	v_exp_f32_e32 v88, v80
	v_exp_f32_e32 v89, v81
	v_exp_f32_e32 v90, v82
	v_exp_f32_e32 v91, v83
	v_mfma_f32_32x32x16_bf16 v[128:143], v[96:99], v[168:171], v[128:143]
	ds_read_b128 v[80:83], v213 offset:224
	v_add_u32_e32 v96, v181, v195
	ds_read_b128 v[84:87], v96
	ds_read_b128 v[232:235], v96 offset:8192
	v_cvt_pk_bf16_f32 v236, v88, v89
	v_cvt_pk_bf16_f32 v237, v90, v91
	s_waitcnt lgkmcnt(0)
	v_pk_add_f32 v[80:81], v[180:181], v[80:81] op_sel_hi:[0,1] neg_lo:[0,1] neg_hi:[0,1]
	v_pk_fma_f32 v[80:81], v[92:93], s[92:93], v[80:81] op_sel_hi:[1,0,1]
	v_pk_add_f32 v[92:93], v[182:183], v[106:107]
	v_pk_add_f32 v[92:93], v[92:93], v[108:109]
	v_pk_add_f32 v[82:83], v[180:181], v[82:83] op_sel_hi:[0,1] neg_lo:[0,1] neg_hi:[0,1]
	v_pk_add_f32 v[92:93], v[110:111], v[92:93]
	v_pk_add_f32 v[92:93], v[92:93], v[104:105]
	v_pk_fma_f32 v[82:83], v[94:95], s[92:93], v[82:83] op_sel_hi:[1,0,1]
	v_pk_add_f32 v[92:93], v[214:215], v[92:93]
	v_exp_f32_e32 v80, v80
	v_exp_f32_e32 v81, v81
	v_pk_add_f32 v[92:93], v[92:93], v[100:101]
	v_exp_f32_e32 v82, v82
	v_exp_f32_e32 v83, v83
	v_pk_add_f32 v[92:93], v[102:103], v[92:93]
	v_pk_add_f32 v[92:93], v[92:93], v[88:89]
	v_pk_add_f32 v[92:93], v[90:91], v[92:93]
	v_pk_add_f32 v[92:93], v[92:93], v[80:81]
	v_pk_add_f32 v[182:183], v[82:83], v[92:93]
	v_cvt_pk_bf16_f32 v238, v80, v81
	v_mfma_f32_32x32x16_bf16 v[96:111], v[84:87], v[172:175], v[112:127]
	v_cvt_pk_bf16_f32 v239, v82, v83
	v_permlane32_swap_b32_e32 v236, v238
	v_mfma_f32_32x32x16_bf16 v[80:95], v[232:235], v[172:175], v[128:143]
	v_permlane32_swap_b32_e32 v237, v239
	v_add_u32_e32 v181, s15, v179
	ds_read_b64_tr_b16 v[112:113], v181 offset:0
	ds_read_b64_tr_b16 v[114:115], v181 offset:0x800
	ds_read_b64_tr_b16 v[116:117], v181 offset:0x1000
	ds_read_b64_tr_b16 v[118:119], v181 offset:0x1800
	ds_read_b64_tr_b16 v[120:121], v181 offset:0x2000
	ds_read_b64_tr_b16 v[122:123], v181 offset:0x2800
	ds_read_b64_tr_b16 v[124:125], v181 offset:0x3000
	ds_read_b64_tr_b16 v[126:127], v181 offset:0x3800
	ds_read_b64_tr_b16 v[128:129], v181 offset:0x200
	ds_read_b64_tr_b16 v[130:131], v181 offset:0xa00
	ds_read_b64_tr_b16 v[132:133], v181 offset:0x1200
	ds_read_b64_tr_b16 v[134:135], v181 offset:0x1a00
	ds_read_b64_tr_b16 v[136:137], v181 offset:0x2200
	ds_read_b64_tr_b16 v[138:139], v181 offset:0x2a00
	ds_read_b64_tr_b16 v[140:141], v181 offset:0x3200
	ds_read_b64_tr_b16 v[142:143], v181 offset:0x3a00
	s_waitcnt lgkmcnt(8)
	s_nop 0
	v_mfma_f32_32x32x16_bf16 v[64:79], v[2:5], v[112:115], v[64:79]
	v_mfma_f32_32x32x16_bf16 v[64:79], v[6:9], v[116:119], v[64:79]
	v_mfma_f32_32x32x16_bf16 v[64:79], v[10:13], v[120:123], v[64:79]
	v_mfma_f32_32x32x16_bf16 v[64:79], v[236:239], v[124:127], v[64:79]
	ds_read_b64_tr_b16 v[112:113], v181 offset:0x400
	ds_read_b64_tr_b16 v[114:115], v181 offset:0xc00
	ds_read_b64_tr_b16 v[116:117], v181 offset:0x1400
	ds_read_b64_tr_b16 v[118:119], v181 offset:0x1c00
	ds_read_b64_tr_b16 v[120:121], v181 offset:0x2400
	ds_read_b64_tr_b16 v[122:123], v181 offset:0x2c00
	ds_read_b64_tr_b16 v[124:125], v181 offset:0x3400
	ds_read_b64_tr_b16 v[126:127], v181 offset:0x3c00
	s_waitcnt lgkmcnt(8)
	v_mfma_f32_32x32x16_bf16 v[48:63], v[2:5], v[128:131], v[48:63]
	v_mfma_f32_32x32x16_bf16 v[48:63], v[6:9], v[132:135], v[48:63]
	v_mfma_f32_32x32x16_bf16 v[48:63], v[10:13], v[136:139], v[48:63]
	v_mfma_f32_32x32x16_bf16 v[48:63], v[236:239], v[140:143], v[48:63]
	ds_read_b64_tr_b16 v[128:129], v181 offset:0x600
	ds_read_b64_tr_b16 v[130:131], v181 offset:0xe00
	ds_read_b64_tr_b16 v[132:133], v181 offset:0x1600
	ds_read_b64_tr_b16 v[134:135], v181 offset:0x1e00
	ds_read_b64_tr_b16 v[136:137], v181 offset:0x2600
	ds_read_b64_tr_b16 v[138:139], v181 offset:0x2e00
	ds_read_b64_tr_b16 v[140:141], v181 offset:0x3600
	ds_read_b64_tr_b16 v[142:143], v181 offset:0x3e00
	s_waitcnt lgkmcnt(8)
	v_mfma_f32_32x32x16_bf16 v[32:47], v[2:5], v[112:115], v[32:47]
	v_mfma_f32_32x32x16_bf16 v[32:47], v[6:9], v[116:119], v[32:47]
	v_mfma_f32_32x32x16_bf16 v[32:47], v[10:13], v[120:123], v[32:47]
	v_mfma_f32_32x32x16_bf16 v[32:47], v[236:239], v[124:127], v[32:47]
	s_waitcnt lgkmcnt(0)
	v_mfma_f32_32x32x16_bf16 v[16:31], v[2:5], v[128:131], v[16:31]
	s_waitcnt vmcnt(5)
	s_barrier
	s_add_i32 s6, s6, 1
	s_cmp_ge_i32 s6, s8
	s_mov_b32 s15, s57
	s_mov_b32 s57, s63
	v_mfma_f32_32x32x16_bf16 v[16:31], v[6:9], v[132:135], v[16:31]
	s_mov_b32 s63, s13
	v_mfma_f32_32x32x16_bf16 v[16:31], v[10:13], v[136:139], v[16:31]
	v_mfma_f32_32x32x16_bf16 v[16:31], v[236:239], v[140:143], v[16:31]
	s_cbranch_scc1 .LBB0_973
